# meta-query attention side path (workgroups 0-7, the P3 stragglers): its three dependent global-load rounds are issued together (second K round and the V loads into spare registers)
# baseline (speedup 1.0000x reference)
; __device__ __forceinline__ float fexp2(float x) { return __builtin_amdgcn_exp2f(x); }
; __device__ __forceinline__ void attn_meta(LAS unsigned char* lds, const bf16_t* Q, const bf16_t* KN, const bf16_t* KPE, const bf16_t* VT, bf16_t* Y, float* ssq_b, int b, int h) {
;     ...
;     if (tid < 256) {
;         const int qi = tid >> 7, k = (tid >> 3) & 15, part = tid & 7;
;         const size_t qrow = (size_t)16384 + 14 + qi, krow = (size_t)16384 + k; float acc = 0.f;
; #pragma unroll
;         for (int i = 0; i < 3; ++i) { const int pc = part * 3 + i;
;             const u32x4 qw = *(const u32x4*)(Q + qrow * 1536 + h * 192 + pc * 8);
;             const u32x4 kw = pc < 16 ? *(const u32x4*)(KN + krow * 1024 + h * 128 + pc * 8) : *(const u32x4*)(KPE + krow * 64 + (pc - 16) * 8);
;             acc += dot8(qw, kw); }
;         acc += __shfl_xor(acc, 1); acc += __shfl_xor(acc, 2); acc += __shfl_xor(acc, 4);
;         if (part == 0) sc[qi * 16 + k] = acc;
;     }
;     __syncthreads();
;     if (tid < 256) {
;         const int qi = tid >> 7, d = tid & 127; const size_t row = (size_t)16384 + qi;
;         float s[16]; float mx = -INFINITY;
; #pragma unroll
;         for (int k = 0; k < 16; ++k) { s[k] = sc[qi * 16 + k]; mx = fmaxf(mx, s[k]); }
;         float l = 0.f;
; #pragma unroll
;         for (int k = 0; k < 16; ++k) { s[k] = fexp2(s[k] - mx); l += s[k]; }
;         const bf16_t* vp = VT + ((size_t)((64 + h) * 128 + d)) * 2048;
;         const u32x4 va = *(const u32x4*)vp, vb = *(const u32x4*)(vp + 8);
.LBB0_711:
	s_and_saveexec_b64 s[10:11], s[48:49]
	s_cbranch_execz .LBB0_714
	s_ashr_i32 s7, s6, 31
	s_ashr_i32 s5, s4, 31
	v_lshl_add_u64 v[14:15], s[6:7], 1, v[10:11]
	global_load_dwordx4 v[24:27], v[14:15], off offset:32
	global_load_dwordx4 v[28:31], v[14:15], off offset:16
	global_load_dwordx4 v[32:35], v[14:15], off
	v_lshl_add_u64 v[14:15], s[4:5], 1, v[12:13]
	v_cndmask_b32_e64 v37, v3, v15, s[52:53]
	v_cndmask_b32_e64 v36, v2, v14, s[52:53]
	global_load_dwordx4 v[36:39], v[36:37], off
	v_lshl_add_u64 v[14:15], v[14:15], 0, 16
	v_cndmask_b32_e64 v15, v5, v15, s[54:55]
	v_cndmask_b32_e64 v14, v4, v14, s[54:55]
	global_load_dwordx4 v[244:247], v[14:15], off offset:16
	global_load_dwordx4 v[248:251], v[14:15], off
	v_add_u32_e32 v108, s4, v0
	v_ashrrev_i32_e32 v109, 31, v108
	v_lshlrev_b64 v[108:109], 12, v[108:109]
	v_lshl_add_u64 v[108:109], s[42:43], 0, v[108:109]
	global_load_dwordx4 v[100:103], v[108:109], off
	global_load_dwordx4 v[104:107], v[108:109], off offset:16
	v_cmp_lt_i32_e32 vcc, v19, v20
	s_waitcnt vmcnt(5)
	v_lshlrev_b32_e32 v23, 16, v32
	v_and_b32_e32 v32, 0xffff0000, v32
	s_waitcnt vmcnt(4)
	v_lshlrev_b32_e32 v40, 16, v36
	v_and_b32_e32 v36, 0xffff0000, v36
	v_mul_f32_e32 v32, v32, v36
	v_fmac_f32_e32 v32, v23, v40
	v_lshlrev_b32_e32 v23, 16, v33
	v_lshlrev_b32_e32 v36, 16, v37
	v_fmac_f32_e32 v32, v23, v36
	v_and_b32_e32 v23, 0xffff0000, v33
	v_and_b32_e32 v33, 0xffff0000, v37
	v_fmac_f32_e32 v32, v23, v33
	v_lshlrev_b32_e32 v23, 16, v34
	v_lshlrev_b32_e32 v33, 16, v38
	v_fmac_f32_e32 v32, v23, v33
	v_and_b32_e32 v23, 0xffff0000, v34
	v_and_b32_e32 v33, 0xffff0000, v38
	v_fmac_f32_e32 v32, v23, v33
	v_lshlrev_b32_e32 v23, 16, v35
	v_lshlrev_b32_e32 v33, 16, v39
	v_fmac_f32_e32 v32, v23, v33
	v_and_b32_e32 v23, 0xffff0000, v35
	v_and_b32_e32 v33, 0xffff0000, v39
	v_fmac_f32_e32 v32, v23, v33
	v_add_f32_e32 v23, 0, v32
	v_lshlrev_b32_e32 v14, 16, v28
	v_and_b32_e32 v28, 0xffff0000, v28
	s_waitcnt vmcnt(2)
	v_lshlrev_b32_e32 v15, 16, v248
	v_and_b32_e32 v248, 0xffff0000, v248
	v_mul_f32_e32 v28, v28, v248
	v_fmac_f32_e32 v28, v14, v15
	v_lshlrev_b32_e32 v14, 16, v29
	v_lshlrev_b32_e32 v15, 16, v249
	v_fmac_f32_e32 v28, v14, v15
	v_and_b32_e32 v14, 0xffff0000, v29
	v_and_b32_e32 v15, 0xffff0000, v249
	v_fmac_f32_e32 v28, v14, v15
	v_lshlrev_b32_e32 v14, 16, v30
	v_lshlrev_b32_e32 v15, 16, v250
	v_fmac_f32_e32 v28, v14, v15
	v_and_b32_e32 v14, 0xffff0000, v30
	v_and_b32_e32 v15, 0xffff0000, v250
	v_fmac_f32_e32 v28, v14, v15
	v_lshlrev_b32_e32 v14, 16, v31
	v_lshlrev_b32_e32 v15, 16, v251
	v_fmac_f32_e32 v28, v14, v15
	v_and_b32_e32 v14, 0xffff0000, v31
	v_and_b32_e32 v15, 0xffff0000, v251
	v_fmac_f32_e32 v28, v14, v15
	v_add_f32_e32 v14, v23, v28
	v_lshlrev_b32_e32 v15, 16, v24
	v_and_b32_e32 v24, 0xffff0000, v24
	v_and_b32_e32 v28, 0xffff0000, v244
	v_lshlrev_b32_e32 v23, 16, v244
	v_mul_f32_e32 v24, v24, v28
	v_fmac_f32_e32 v24, v15, v23
	v_lshlrev_b32_e32 v15, 16, v25
	v_lshlrev_b32_e32 v23, 16, v245
	v_fmac_f32_e32 v24, v15, v23
	v_and_b32_e32 v15, 0xffff0000, v25
	v_and_b32_e32 v23, 0xffff0000, v245
	v_fmac_f32_e32 v24, v15, v23
	v_lshlrev_b32_e32 v15, 16, v26
	v_lshlrev_b32_e32 v23, 16, v246
	v_fmac_f32_e32 v24, v15, v23
	v_and_b32_e32 v15, 0xffff0000, v26
	v_and_b32_e32 v23, 0xffff0000, v246
	v_fmac_f32_e32 v24, v15, v23
	v_lshlrev_b32_e32 v15, 16, v27
	v_lshlrev_b32_e32 v23, 16, v247
	v_fmac_f32_e32 v24, v15, v23
	v_and_b32_e32 v15, 0xffff0000, v27
	v_and_b32_e32 v23, 0xffff0000, v247
	v_fmac_f32_e32 v24, v15, v23
	v_cndmask_b32_e32 v15, v18, v19, vcc
	v_add_f32_e32 v14, v14, v24
	v_lshlrev_b32_e32 v15, 2, v15
	ds_bpermute_b32 v15, v15, v14
	v_cmp_lt_i32_e32 vcc, v21, v20
	s_waitcnt lgkmcnt(0)
	v_add_f32_e32 v14, v14, v15
	v_cndmask_b32_e32 v15, v18, v21, vcc
	v_lshlrev_b32_e32 v15, 2, v15
	ds_bpermute_b32 v15, v15, v14
	v_cmp_lt_i32_e32 vcc, v22, v20
	s_waitcnt lgkmcnt(0)
	v_add_f32_e32 v14, v14, v15
	v_cndmask_b32_e32 v15, v18, v22, vcc
	v_lshlrev_b32_e32 v15, 2, v15
	ds_bpermute_b32 v15, v15, v14
	s_and_b64 exec, exec, s[56:57]
	s_cbranch_execz .LBB0_714
	s_waitcnt lgkmcnt(0)
	v_add_f32_e32 v14, v14, v15
	ds_write_b32 v17, v14
; __device__ __forceinline__ unsigned cvt_pk(float lo, float hi) { unsigned r; asm volatile("v_cvt_pk_bf16_f32 %0, %1, %2" : "=v"(r) : "v"(lo), "v"(hi)); return r; }
; __device__ __forceinline__ float fexp2(float x) { return __builtin_amdgcn_exp2f(x); }
; __device__ __forceinline__ void attn_meta(LAS unsigned char* lds, const bf16_t* Q, const bf16_t* KN, const bf16_t* KPE, const bf16_t* VT, bf16_t* Y, float* ssq_b, int b, int h) {
;     ...
;     __syncthreads();
;     if (tid < 256) {
;         const int qi = tid >> 7, d = tid & 127; const size_t row = (size_t)16384 + qi;
;         float s[16]; float mx = -INFINITY;
; #pragma unroll
;         for (int k = 0; k < 16; ++k) { s[k] = sc[qi * 16 + k]; mx = fmaxf(mx, s[k]); }
;         float l = 0.f;
; #pragma unroll
;         for (int k = 0; k < 16; ++k) { s[k] = fexp2(s[k] - mx); l += s[k]; }
;         const bf16_t* vp = VT + ((size_t)((64 + h) * 128 + d)) * 2048;
;         const u32x4 va = *(const u32x4*)vp, vb = *(const u32x4*)(vp + 8);
;         float a = s[0] * __builtin_bit_cast(float, va.x << 16) + s[1] * __builtin_bit_cast(float, va.x & 0xffff0000u) + s[2] * __builtin_bit_cast(float, va.y << 16) + s[3] * __builtin_bit_cast(float, va.y & 0xffff0000u)
;                 + s[4] * __builtin_bit_cast(float, va.z << 16) + s[5] * __builtin_bit_cast(float, va.z & 0xffff0000u) + s[6] * __builtin_bit_cast(float, va.w << 16) + s[7] * __builtin_bit_cast(float, va.w & 0xffff0000u)
;                 + s[8] * __builtin_bit_cast(float, vb.x << 16) + s[9] * __builtin_bit_cast(float, vb.x & 0xffff0000u) + s[10] * __builtin_bit_cast(float, vb.y << 16) + s[11] * __builtin_bit_cast(float, vb.y & 0xffff0000u)
;                 + s[12] * __builtin_bit_cast(float, vb.z << 16) + s[13] * __builtin_bit_cast(float, vb.z & 0xffff0000u) + s[14] * __builtin_bit_cast(float, vb.w << 16) + s[15] * __builtin_bit_cast(float, vb.w & 0xffff0000u);
;         a = a / l;
;         Y[row * 2048 + 1024 + h * 128 + d] = (bf16_t)(cvt_pk(a, 0.f) & 0xffff);
;         const float ss = wave_sum(a * a);
;         if ((tid & 63) == 0 && ssq_b) atomicAdd(ssq_b + row, ss);
.LBB0_714:
	s_or_b64 exec, exec, s[10:11]
	s_waitcnt lgkmcnt(0)
	s_barrier
	s_and_saveexec_b64 s[10:11], s[48:49]
	s_cbranch_execz .LBB0_710
	v_add_u32_e32 v14, s4, v0
	v_ashrrev_i32_e32 v15, 31, v14
	v_lshlrev_b64 v[14:15], 12, v[14:15]
	v_lshl_add_u64 v[14:15], s[42:43], 0, v[14:15]
	ds_read_b128 v[32:35], v16
	ds_read_b128 v[36:39], v16 offset:16
	ds_read_b128 v[40:43], v16 offset:32
	ds_read_b128 v[44:47], v16 offset:48
	s_mov_b32 s5, 0xff800000
	s_waitcnt lgkmcnt(3)
	v_max3_f32 v14, v32, s5, v33
	v_max3_f32 v14, v14, v34, v35
	s_waitcnt lgkmcnt(2)
	v_max3_f32 v14, v14, v36, v37
	v_max3_f32 v14, v14, v38, v39
	s_waitcnt lgkmcnt(1)
	v_max3_f32 v14, v14, v40, v41
	v_max3_f32 v14, v14, v42, v43
	s_waitcnt lgkmcnt(0)
	v_max3_f32 v14, v14, v44, v45
	v_max3_f32 v14, v14, v46, v47
	v_sub_f32_e32 v15, v32, v14
	v_sub_f32_e32 v23, v33, v14
	v_sub_f32_e32 v32, v34, v14
	v_exp_f32_e32 v54, v15
	v_exp_f32_e32 v15, v23
	v_sub_f32_e32 v34, v35, v14
	v_exp_f32_e32 v33, v32
	v_sub_f32_e32 v36, v36, v14
	v_sub_f32_e32 v48, v37, v14
	v_sub_f32_e32 v38, v38, v14
	v_sub_f32_e32 v49, v39, v14
	v_sub_f32_e32 v40, v40, v14
	v_sub_f32_e32 v50, v41, v14
	v_sub_f32_e32 v42, v42, v14
	v_sub_f32_e32 v51, v43, v14
	v_sub_f32_e32 v44, v44, v14
	v_sub_f32_e32 v52, v45, v14
	v_sub_f32_e32 v46, v46, v14
	v_sub_f32_e32 v14, v47, v14
	v_exp_f32_e32 v35, v34
	v_exp_f32_e32 v37, v36
	v_exp_f32_e32 v59, v14
	v_exp_f32_e32 v39, v48
	v_add_f32_e32 v61, 0, v54
	v_exp_f32_e32 v41, v38
	v_exp_f32_e32 v43, v49
	v_exp_f32_e32 v45, v40
	v_exp_f32_e32 v47, v50
	v_exp_f32_e32 v49, v42
	v_exp_f32_e32 v51, v51
	v_exp_f32_e32 v53, v44
	v_exp_f32_e32 v55, v52
	v_exp_f32_e32 v57, v46
	v_cmp_lt_i32_e32 vcc, v19, v20
	s_ashr_i32 s5, s4, 31
	s_waitcnt vmcnt(1)
	v_lshlrev_b32_e32 v14, 16, v100
	v_and_b32_e32 v23, 0xffff0000, v100
	v_lshlrev_b32_e32 v100, 16, v101
	v_mul_f32_e32 v60, v54, v14
	v_mul_f32_e32 v14, v15, v23
	v_and_b32_e32 v101, 0xffff0000, v101
	v_mul_f32_e32 v32, v33, v100
	v_pk_add_f32 v[14:15], v[14:15], v[60:61]
	v_lshlrev_b32_e32 v36, 16, v102
	v_mul_f32_e32 v34, v35, v101
	v_pk_add_f32 v[14:15], v[32:33], v[14:15]
	v_and_b32_e32 v102, 0xffff0000, v102
	v_mul_f32_e32 v36, v37, v36
	v_pk_add_f32 v[14:15], v[34:35], v[14:15]
	v_lshlrev_b32_e32 v40, 16, v103
	v_mul_f32_e32 v38, v39, v102
	v_pk_add_f32 v[14:15], v[36:37], v[14:15]
	v_and_b32_e32 v103, 0xffff0000, v103
	v_mul_f32_e32 v40, v41, v40
	v_pk_add_f32 v[14:15], v[38:39], v[14:15]
	s_waitcnt vmcnt(0)
	v_lshlrev_b32_e32 v44, 16, v104
	v_mul_f32_e32 v42, v43, v103
	v_pk_add_f32 v[14:15], v[40:41], v[14:15]
	v_and_b32_e32 v104, 0xffff0000, v104
	v_mul_f32_e32 v44, v45, v44
	v_pk_add_f32 v[14:15], v[42:43], v[14:15]
	v_lshlrev_b32_e32 v48, 16, v105
	v_mul_f32_e32 v46, v47, v104
	v_pk_add_f32 v[14:15], v[44:45], v[14:15]
	v_and_b32_e32 v105, 0xffff0000, v105
	v_mul_f32_e32 v48, v49, v48
	v_pk_add_f32 v[14:15], v[46:47], v[14:15]
	v_lshlrev_b32_e32 v52, 16, v106
	v_mul_f32_e32 v50, v51, v105
	v_pk_add_f32 v[14:15], v[48:49], v[14:15]
	v_and_b32_e32 v106, 0xffff0000, v106
	v_mul_f32_e32 v52, v53, v52
	v_pk_add_f32 v[14:15], v[50:51], v[14:15]
	v_lshlrev_b32_e32 v56, 16, v107
	v_mul_f32_e32 v54, v55, v106
	v_pk_add_f32 v[14:15], v[52:53], v[14:15]
	v_and_b32_e32 v107, 0xffff0000, v107
	v_mul_f32_e32 v56, v57, v56
	v_pk_add_f32 v[14:15], v[54:55], v[14:15]
	v_mul_f32_e32 v58, v59, v107
	v_pk_add_f32 v[14:15], v[56:57], v[14:15]
	v_cndmask_b32_e32 v25, v18, v19, vcc
	v_pk_add_f32 v[14:15], v[58:59], v[14:15]
	s_nop 0
	v_div_scale_f32 v23, s[12:13], v15, v15, v14
	v_rcp_f32_e32 v24, v23
	v_div_scale_f32 v26, vcc, v14, v15, v14
	v_fma_f32 v27, -v23, v24, 1.0
	v_fmac_f32_e32 v24, v27, v24
	v_mul_f32_e32 v27, v26, v24
	v_fma_f32 v28, -v23, v27, v26
	v_fmac_f32_e32 v27, v28, v24
	v_fma_f32 v23, -v23, v27, v26
	v_div_fmas_f32 v23, v23, v24, v27
	v_div_fixup_f32 v23, v23, v15, v14
	v_mul_f32_e32 v14, v23, v23
	v_lshlrev_b32_e32 v15, 2, v25
	ds_bpermute_b32 v14, v15, v14
	v_cmp_lt_i32_e32 vcc, v21, v20
	s_waitcnt lgkmcnt(0)
	v_fmac_f32_e32 v14, v23, v23
	v_cndmask_b32_e32 v15, v18, v21, vcc
	v_lshlrev_b32_e32 v15, 2, v15
	ds_bpermute_b32 v15, v15, v14
	v_cmp_lt_i32_e32 vcc, v22, v20
	v_cvt_pk_bf16_f32 v23, v23, v1
	s_waitcnt lgkmcnt(0)
	v_add_f32_e32 v14, v14, v15
	v_cndmask_b32_e32 v24, v18, v22, vcc
	v_lshlrev_b32_e32 v24, 2, v24
	ds_bpermute_b32 v15, v24, v14
	v_xor_b32_e32 v24, 8, v18
	v_cmp_lt_i32_e32 vcc, v24, v20
	s_waitcnt lgkmcnt(0)
	v_add_f32_e32 v14, v14, v15
	v_cndmask_b32_e32 v24, v18, v24, vcc
	v_lshlrev_b32_e32 v24, 2, v24
	ds_bpermute_b32 v15, v24, v14
	v_xor_b32_e32 v24, 16, v18
	v_cmp_lt_i32_e32 vcc, v24, v20
	s_waitcnt lgkmcnt(0)
	v_add_f32_e32 v14, v14, v15
	v_cndmask_b32_e32 v24, v18, v24, vcc
	v_lshlrev_b32_e32 v24, 2, v24
	ds_bpermute_b32 v15, v24, v14
	v_xor_b32_e32 v24, 32, v18
	v_cmp_lt_i32_e32 vcc, v24, v20
	s_waitcnt lgkmcnt(0)
	v_add_f32_e32 v14, v14, v15
	v_cndmask_b32_e32 v24, v18, v24, vcc
	v_lshlrev_b32_e32 v15, 2, v24
	ds_bpermute_b32 v15, v15, v14
	v_lshl_add_u64 v[24:25], s[4:5], 1, v[6:7]
	global_store_short v[24:25], v23, off offset:2048
	s_and_b64 exec, exec, s[40:41]
	s_cbranch_execz .LBB0_710
	s_waitcnt lgkmcnt(0)
	v_add_f32_e32 v14, v14, v15
	global_atomic_add_f32 v[8:9], v14, off
	s_branch .LBB0_710
